# prep step 3 (kk->M, qk->AC) rewritten with batched LDS reads
# speedup vs baseline: 1.0270x; 1.0047x over previous
.LBB0_218:
	s_or_b64 exec, exec, s[0:1]
	s_waitcnt lgkmcnt(0)
	s_barrier
	v_add_u32_e32 v13, s88, v234
	v_add_u32_e32 v13, 0x21600, v13
	v_add_u32_e32 v11, v234, v233
	v_add_u32_e32 v14, v234, v232
	ds_read_b128 v[16:19], v13 offset:256
	ds_read_b128 v[20:23], v13 offset:272
	ds_read_b128 v[24:27], v13 offset:512
	ds_read_b128 v[28:31], v13 offset:528
	ds_read_b128 v[32:35], v13 offset:0
	ds_read_b128 v[36:39], v13 offset:16
	ds_read_b64 v[40:41], v11 offset:0
	ds_read_b64 v[42:43], v11 offset:528
	ds_read_b64 v[44:45], v11 offset:1056
	ds_read_b64 v[46:47], v11 offset:1584
	ds_read_b64 v[48:49], v11 offset:2112
	ds_read_b64 v[50:51], v11 offset:2640
	ds_read_b64 v[52:53], v11 offset:3168
	ds_read_b64 v[54:55], v11 offset:3696
	ds_read_b64 v[56:57], v11 offset:33792
	ds_read_b64 v[58:59], v11 offset:34320
	ds_read_b64 v[60:61], v11 offset:34848
	ds_read_b64 v[62:63], v11 offset:35376
	ds_read_b64 v[64:65], v11 offset:35904
	ds_read_b64 v[66:67], v11 offset:36432
	ds_read_b64 v[68:69], v11 offset:36960
	ds_read_b64 v[70:71], v11 offset:37488
	v_add_u32_e32 v9, 0x18c00, v14
	v_add_u32_e32 v10, 0x1d000, v14
	s_mov_b32 s29, 0x15c00000
	v_add_co_u32_e32 v4, vcc, s29, v122
	s_nop 1
	v_addc_co_u32_e32 v5, vcc, 0, v123, vcc
	s_waitcnt lgkmcnt(15)
	v_add_f32_e32 v16, 0x358637bd, v16
	v_add_f32_e32 v17, 0x358637bd, v17
	v_add_f32_e32 v18, 0x358637bd, v18
	v_add_f32_e32 v19, 0x358637bd, v19
	v_add_f32_e32 v20, 0x358637bd, v20
	v_add_f32_e32 v21, 0x358637bd, v21
	v_add_f32_e32 v22, 0x358637bd, v22
	v_add_f32_e32 v23, 0x358637bd, v23
	v_add_f32_e32 v24, 0x358637bd, v24
	v_add_f32_e32 v25, 0x358637bd, v25
	v_add_f32_e32 v26, 0x358637bd, v26
	v_add_f32_e32 v27, 0x358637bd, v27
	v_add_f32_e32 v28, 0x358637bd, v28
	v_add_f32_e32 v29, 0x358637bd, v29
	v_add_f32_e32 v30, 0x358637bd, v30
	v_add_f32_e32 v31, 0x358637bd, v31
	v_rsq_f32_e32 v16, v16
	v_rsq_f32_e32 v17, v17
	v_rsq_f32_e32 v18, v18
	v_rsq_f32_e32 v19, v19
	v_rsq_f32_e32 v20, v20
	v_rsq_f32_e32 v21, v21
	v_rsq_f32_e32 v22, v22
	v_rsq_f32_e32 v23, v23
	v_rsq_f32_e32 v24, v24
	v_rsq_f32_e32 v25, v25
	v_rsq_f32_e32 v26, v26
	v_rsq_f32_e32 v27, v27
	v_rsq_f32_e32 v28, v28
	v_rsq_f32_e32 v29, v29
	v_rsq_f32_e32 v30, v30
	v_rsq_f32_e32 v31, v31
	v_mul_f32_e32 v16, 0x3db504f3, v16
	v_mul_f32_e32 v17, 0x3db504f3, v17
	v_mul_f32_e32 v18, 0x3db504f3, v18
	v_mul_f32_e32 v19, 0x3db504f3, v19
	v_mul_f32_e32 v20, 0x3db504f3, v20
	v_mul_f32_e32 v21, 0x3db504f3, v21
	v_mul_f32_e32 v22, 0x3db504f3, v22
	v_mul_f32_e32 v23, 0x3db504f3, v23
	s_waitcnt lgkmcnt(7)
	v_mul_f32_e32 v40, v40, v16
	v_mul_f32_e32 v41, v41, v16
	v_mul_f32_e32 v56, v56, v24
	v_mul_f32_e32 v57, v57, v24
	v_cvt_pk_bf16_f32 v6, v40, v41
	v_cvt_pk_bf16_f32 v7, v56, v57
	v_mul_f32_e32 v40, v40, v32
	v_mul_f32_e32 v41, v41, v32
	ds_write_b32 v9, v6 offset:0
	ds_write_b32 v10, v7 offset:0
	ds_write_b64 v11, v[56:57] offset:33792
	v_cvt_pk_bf16_f32 v8, v40, v41
	global_store_dword v[4:5], v8, off offset:0
	s_waitcnt lgkmcnt(9)
	v_mul_f32_e32 v42, v42, v17
	v_mul_f32_e32 v43, v43, v17
	v_mul_f32_e32 v58, v58, v25
	v_mul_f32_e32 v59, v59, v25
	v_cvt_pk_bf16_f32 v6, v42, v43
	v_cvt_pk_bf16_f32 v7, v58, v59
	v_mul_f32_e32 v42, v42, v33
	v_mul_f32_e32 v43, v43, v33
	ds_write_b32 v9, v6 offset:272
	ds_write_b32 v10, v7 offset:272
	ds_write_b64 v11, v[58:59] offset:34320
	v_cvt_pk_bf16_f32 v8, v42, v43
	global_store_dword v[4:5], v8, off offset:256
	s_waitcnt lgkmcnt(11)
	v_mul_f32_e32 v44, v44, v18
	v_mul_f32_e32 v45, v45, v18
	v_mul_f32_e32 v60, v60, v26
	v_mul_f32_e32 v61, v61, v26
	v_cvt_pk_bf16_f32 v6, v44, v45
	v_cvt_pk_bf16_f32 v7, v60, v61
	v_mul_f32_e32 v44, v44, v34
	v_mul_f32_e32 v45, v45, v34
	ds_write_b32 v9, v6 offset:544
	ds_write_b32 v10, v7 offset:544
	ds_write_b64 v11, v[60:61] offset:34848
	v_cvt_pk_bf16_f32 v8, v44, v45
	global_store_dword v[4:5], v8, off offset:512
	s_waitcnt lgkmcnt(13)
	v_mul_f32_e32 v46, v46, v19
	v_mul_f32_e32 v47, v47, v19
	v_mul_f32_e32 v62, v62, v27
	v_mul_f32_e32 v63, v63, v27
	v_cvt_pk_bf16_f32 v6, v46, v47
	v_cvt_pk_bf16_f32 v7, v62, v63
	v_mul_f32_e32 v46, v46, v35
	v_mul_f32_e32 v47, v47, v35
	ds_write_b32 v9, v6 offset:816
	ds_write_b32 v10, v7 offset:816
	ds_write_b64 v11, v[62:63] offset:35376
	v_cvt_pk_bf16_f32 v8, v46, v47
	global_store_dword v[4:5], v8, off offset:768
	s_waitcnt lgkmcnt(15)
	v_mul_f32_e32 v48, v48, v20
	v_mul_f32_e32 v49, v49, v20
	v_mul_f32_e32 v64, v64, v28
	v_mul_f32_e32 v65, v65, v28
	v_cvt_pk_bf16_f32 v6, v48, v49
	v_cvt_pk_bf16_f32 v7, v64, v65
	v_mul_f32_e32 v48, v48, v36
	v_mul_f32_e32 v49, v49, v36
	ds_write_b32 v9, v6 offset:1088
	ds_write_b32 v10, v7 offset:1088
	ds_write_b64 v11, v[64:65] offset:35904
	v_cvt_pk_bf16_f32 v8, v48, v49
	global_store_dword v[4:5], v8, off offset:1024
	s_waitcnt lgkmcnt(15)
	v_mul_f32_e32 v50, v50, v21
	v_mul_f32_e32 v51, v51, v21
	v_mul_f32_e32 v66, v66, v29
	v_mul_f32_e32 v67, v67, v29
	v_cvt_pk_bf16_f32 v6, v50, v51
	v_cvt_pk_bf16_f32 v7, v66, v67
	v_mul_f32_e32 v50, v50, v37
	v_mul_f32_e32 v51, v51, v37
	ds_write_b32 v9, v6 offset:1360
	ds_write_b32 v10, v7 offset:1360
	ds_write_b64 v11, v[66:67] offset:36432
	v_cvt_pk_bf16_f32 v8, v50, v51
	global_store_dword v[4:5], v8, off offset:1280
	v_mul_f32_e32 v52, v52, v22
	v_mul_f32_e32 v53, v53, v22
	v_mul_f32_e32 v68, v68, v30
	v_mul_f32_e32 v69, v69, v30
	v_cvt_pk_bf16_f32 v6, v52, v53
	v_cvt_pk_bf16_f32 v7, v68, v69
	v_mul_f32_e32 v52, v52, v38
	v_mul_f32_e32 v53, v53, v38
	ds_write_b32 v9, v6 offset:1632
	ds_write_b32 v10, v7 offset:1632
	ds_write_b64 v11, v[68:69] offset:36960
	v_cvt_pk_bf16_f32 v8, v52, v53
	global_store_dword v[4:5], v8, off offset:1536
	v_mul_f32_e32 v54, v54, v23
	v_mul_f32_e32 v55, v55, v23
	v_mul_f32_e32 v70, v70, v31
	v_mul_f32_e32 v71, v71, v31
	v_cvt_pk_bf16_f32 v6, v54, v55
	v_cvt_pk_bf16_f32 v7, v70, v71
	v_mul_f32_e32 v54, v54, v39
	v_mul_f32_e32 v55, v55, v39
	ds_write_b32 v9, v6 offset:1904
	ds_write_b32 v10, v7 offset:1904
	ds_write_b64 v11, v[70:71] offset:37488
	v_cvt_pk_bf16_f32 v8, v54, v55
	global_store_dword v[4:5], v8, off offset:1792
	s_add_i32 s28, s88, 32
	s_mov_b32 s1, 0
	s_movk_i32 s0, 0x800
	s_cmpk_eq_i32 s0, 0x800
	v_add_u32_e32 v28, 0x18c00, v234
	s_waitcnt lgkmcnt(0)
	s_barrier
	s_ashr_i32 s65, s64, 31
	s_lshr_b32 s28, s88, 5
	s_and_b32 s28, s28, 3
	v_and_b32_e32 v154, 15, v160
	v_lshrrev_b32_e32 v155, 4, v160
	v_mul_u32_u24_e32 v156, 0x110, v154
	v_lshl_add_u32 v156, v155, 4, v156
	v_add_u32_e32 v167, 0x1d000, v234
	v_add_u32_e32 v167, v167, v156
	s_mul_i32 s29, s28, 0x1100
	v_add_u32_e32 v157, s29, v167
	s_lshl_b32 s29, s28, 6
	v_lshl_add_u32 v169, v155, 4, v234
	v_add_u32_e32 v169, 0x21400, v169
	v_add_u32_e32 v169, s29, v169
	v_lshl_add_u32 v170, v154, 2, v234
	v_add_u32_e32 v170, 0x21500, v170
	v_lshlrev_b32_e32 v156, 2, v155
	v_sub_u32_e32 v172, v154, v156
	v_subrev_u32_e32 v173, 1, v172
	v_subrev_u32_e32 v174, 2, v172
	v_subrev_u32_e32 v175, 3, v172
	s_cmp_lt_u32 s88, 0x80
	s_cbranch_scc0 .Lp3_w1
	v_mul_u32_u24_e32 v171, 0x440, v155
	v_lshl_add_u32 v171, v154, 2, v171
	s_mul_i32 s29, s28, 0x1100
	v_add3_u32 v171, v171, v234, s29
	ds_read_b128 v[4:7], v157 offset:0
	ds_read_b128 v[8:11], v157 offset:64
	ds_read_b128 v[12:15], v157 offset:128
	ds_read_b128 v[16:19], v157 offset:192
	ds_read_b128 v[24:27], v169 offset:256
	ds_read_b128 v[244:247], v169
	ds_read_b32 v146, v170 offset:0
	ds_read_b32 v147, v170 offset:64
	ds_read_b32 v148, v170 offset:128
	ds_read_b32 v149, v170 offset:192
	ds_read_b128 v[32:35], v167 offset:0
	ds_read_b128 v[36:39], v167 offset:64
	ds_read_b128 v[40:43], v167 offset:128
	ds_read_b128 v[44:47], v167 offset:192
	s_cmp_lt_u32 s28, 1
	s_cbranch_scc1 .Lp3_w0_a
	ds_read_b128 v[48:51], v167 offset:4352
	ds_read_b128 v[52:55], v167 offset:4416
	ds_read_b128 v[56:59], v167 offset:4480
	ds_read_b128 v[60:63], v167 offset:4544
.Lp3_w0_a:
	s_waitcnt lgkmcnt(0)
	v_mfma_f32_16x16x32_bf16 v[64:67], v[4:7], v[32:35], 0
	v_mfma_f32_16x16x32_bf16 v[64:67], v[8:11], v[36:39], v[64:67]
	v_mfma_f32_16x16x32_bf16 v[64:67], v[12:15], v[40:43], v[64:67]
	v_mfma_f32_16x16x32_bf16 v[64:67], v[16:19], v[44:47], v[64:67]
	s_cmp_lt_u32 s28, 1
	s_cbranch_scc1 .Lp3_w0_b
	v_mfma_f32_16x16x32_bf16 v[68:71], v[4:7], v[48:51], 0
	v_mfma_f32_16x16x32_bf16 v[68:71], v[8:11], v[52:55], v[68:71]
	v_mfma_f32_16x16x32_bf16 v[68:71], v[12:15], v[56:59], v[68:71]
	v_mfma_f32_16x16x32_bf16 v[68:71], v[16:19], v[60:63], v[68:71]
.Lp3_w0_b:
	s_cmp_lt_u32 s28, 2
	s_cbranch_scc1 .Lp3_w0_d
	ds_read_b128 v[32:35], v167 offset:8704
	ds_read_b128 v[36:39], v167 offset:8768
	ds_read_b128 v[40:43], v167 offset:8832
	ds_read_b128 v[44:47], v167 offset:8896
	s_cmp_lt_u32 s28, 3
	s_cbranch_scc1 .Lp3_w0_d
	ds_read_b128 v[48:51], v167 offset:13056
	ds_read_b128 v[52:55], v167 offset:13120
	ds_read_b128 v[56:59], v167 offset:13184
	ds_read_b128 v[60:63], v167 offset:13248
.Lp3_w0_d:
	s_nop 7
	s_sub_i32 s29, s28, 0
	s_lshl_b32 s29, s29, 4
	v_sub_f32_e32 v29, v24, v146
	v_sub_f32_e32 v30, v25, v146
	v_sub_f32_e32 v31, v26, v146
	v_sub_f32_e32 v76, v27, v146
	v_min_f32_e32 v29, 0, v29
	v_min_f32_e32 v30, 0, v30
	v_min_f32_e32 v31, 0, v31
	v_min_f32_e32 v76, 0, v76
	v_mul_f32_e32 v29, 0x3fb8aa3b, v29
	v_mul_f32_e32 v30, 0x3fb8aa3b, v30
	v_mul_f32_e32 v31, 0x3fb8aa3b, v31
	v_mul_f32_e32 v76, 0x3fb8aa3b, v76
	v_exp_f32_e32 v29, v29
	v_exp_f32_e32 v30, v30
	v_exp_f32_e32 v31, v31
	v_exp_f32_e32 v76, v76
	v_mul_f32_e32 v77, v244, v64
	v_mul_f32_e32 v176, v245, v65
	v_mul_f32_e32 v177, v246, v66
	v_mul_f32_e32 v198, v247, v67
	v_mul_f32_e32 v77, v77, v29
	v_mul_f32_e32 v176, v176, v30
	v_mul_f32_e32 v177, v177, v31
	v_mul_f32_e32 v198, v198, v76
	v_cmp_gt_i32_e32 vcc, s29, v172
	s_nop 1
	v_cndmask_b32_e32 v77, 0, v77, vcc
	v_cmp_gt_i32_e32 vcc, s29, v173
	s_nop 1
	v_cndmask_b32_e32 v176, 0, v176, vcc
	v_cmp_gt_i32_e32 vcc, s29, v174
	s_nop 1
	v_cndmask_b32_e32 v177, 0, v177, vcc
	v_cmp_gt_i32_e32 vcc, s29, v175
	s_nop 1
	v_cndmask_b32_e32 v198, 0, v198, vcc
	ds_write_b32 v171, v77 offset:0
	ds_write_b32 v171, v176 offset:272
	ds_write_b32 v171, v177 offset:544
	ds_write_b32 v171, v198 offset:816
	s_cmp_lt_u32 s28, 1
	s_cbranch_scc1 .Lp3_w0_done
	s_sub_i32 s29, s28, 1
	s_lshl_b32 s29, s29, 4
	v_sub_f32_e32 v29, v24, v147
	v_sub_f32_e32 v30, v25, v147
	v_sub_f32_e32 v31, v26, v147
	v_sub_f32_e32 v76, v27, v147
	v_min_f32_e32 v29, 0, v29
	v_min_f32_e32 v30, 0, v30
	v_min_f32_e32 v31, 0, v31
	v_min_f32_e32 v76, 0, v76
	v_mul_f32_e32 v29, 0x3fb8aa3b, v29
	v_mul_f32_e32 v30, 0x3fb8aa3b, v30
	v_mul_f32_e32 v31, 0x3fb8aa3b, v31
	v_mul_f32_e32 v76, 0x3fb8aa3b, v76
	v_exp_f32_e32 v29, v29
	v_exp_f32_e32 v30, v30
	v_exp_f32_e32 v31, v31
	v_exp_f32_e32 v76, v76
	v_mul_f32_e32 v77, v244, v68
	v_mul_f32_e32 v176, v245, v69
	v_mul_f32_e32 v177, v246, v70
	v_mul_f32_e32 v198, v247, v71
	v_mul_f32_e32 v77, v77, v29
	v_mul_f32_e32 v176, v176, v30
	v_mul_f32_e32 v177, v177, v31
	v_mul_f32_e32 v198, v198, v76
	v_cmp_gt_i32_e32 vcc, s29, v172
	s_nop 1
	v_cndmask_b32_e32 v77, 0, v77, vcc
	v_cmp_gt_i32_e32 vcc, s29, v173
	s_nop 1
	v_cndmask_b32_e32 v176, 0, v176, vcc
	v_cmp_gt_i32_e32 vcc, s29, v174
	s_nop 1
	v_cndmask_b32_e32 v177, 0, v177, vcc
	v_cmp_gt_i32_e32 vcc, s29, v175
	s_nop 1
	v_cndmask_b32_e32 v198, 0, v198, vcc
	ds_write_b32 v171, v77 offset:64
	ds_write_b32 v171, v176 offset:336
	ds_write_b32 v171, v177 offset:608
	ds_write_b32 v171, v198 offset:880
	s_cmp_lt_u32 s28, 2
	s_cbranch_scc1 .Lp3_w0_done
	s_waitcnt lgkmcnt(0)
	v_mfma_f32_16x16x32_bf16 v[72:75], v[4:7], v[32:35], 0
	v_mfma_f32_16x16x32_bf16 v[72:75], v[8:11], v[36:39], v[72:75]
	v_mfma_f32_16x16x32_bf16 v[72:75], v[12:15], v[40:43], v[72:75]
	v_mfma_f32_16x16x32_bf16 v[72:75], v[16:19], v[44:47], v[72:75]
	s_cmp_lt_u32 s28, 3
	s_cbranch_scc1 .Lp3_w0_f
	v_mfma_f32_16x16x32_bf16 v[20:23], v[4:7], v[48:51], 0
	v_mfma_f32_16x16x32_bf16 v[20:23], v[8:11], v[52:55], v[20:23]
	v_mfma_f32_16x16x32_bf16 v[20:23], v[12:15], v[56:59], v[20:23]
	v_mfma_f32_16x16x32_bf16 v[20:23], v[16:19], v[60:63], v[20:23]
.Lp3_w0_f:
	s_nop 7
	s_sub_i32 s29, s28, 2
	s_lshl_b32 s29, s29, 4
	v_sub_f32_e32 v29, v24, v148
	v_sub_f32_e32 v30, v25, v148
	v_sub_f32_e32 v31, v26, v148
	v_sub_f32_e32 v76, v27, v148
	v_min_f32_e32 v29, 0, v29
	v_min_f32_e32 v30, 0, v30
	v_min_f32_e32 v31, 0, v31
	v_min_f32_e32 v76, 0, v76
	v_mul_f32_e32 v29, 0x3fb8aa3b, v29
	v_mul_f32_e32 v30, 0x3fb8aa3b, v30
	v_mul_f32_e32 v31, 0x3fb8aa3b, v31
	v_mul_f32_e32 v76, 0x3fb8aa3b, v76
	v_exp_f32_e32 v29, v29
	v_exp_f32_e32 v30, v30
	v_exp_f32_e32 v31, v31
	v_exp_f32_e32 v76, v76
	v_mul_f32_e32 v77, v244, v72
	v_mul_f32_e32 v176, v245, v73
	v_mul_f32_e32 v177, v246, v74
	v_mul_f32_e32 v198, v247, v75
	v_mul_f32_e32 v77, v77, v29
	v_mul_f32_e32 v176, v176, v30
	v_mul_f32_e32 v177, v177, v31
	v_mul_f32_e32 v198, v198, v76
	v_cmp_gt_i32_e32 vcc, s29, v172
	s_nop 1
	v_cndmask_b32_e32 v77, 0, v77, vcc
	v_cmp_gt_i32_e32 vcc, s29, v173
	s_nop 1
	v_cndmask_b32_e32 v176, 0, v176, vcc
	v_cmp_gt_i32_e32 vcc, s29, v174
	s_nop 1
	v_cndmask_b32_e32 v177, 0, v177, vcc
	v_cmp_gt_i32_e32 vcc, s29, v175
	s_nop 1
	v_cndmask_b32_e32 v198, 0, v198, vcc
	ds_write_b32 v171, v77 offset:128
	ds_write_b32 v171, v176 offset:400
	ds_write_b32 v171, v177 offset:672
	ds_write_b32 v171, v198 offset:944
	s_cmp_lt_u32 s28, 3
	s_cbranch_scc1 .Lp3_w0_done
	s_sub_i32 s29, s28, 3
	s_lshl_b32 s29, s29, 4
	v_sub_f32_e32 v29, v24, v149
	v_sub_f32_e32 v30, v25, v149
	v_sub_f32_e32 v31, v26, v149
	v_sub_f32_e32 v76, v27, v149
	v_min_f32_e32 v29, 0, v29
	v_min_f32_e32 v30, 0, v30
	v_min_f32_e32 v31, 0, v31
	v_min_f32_e32 v76, 0, v76
	v_mul_f32_e32 v29, 0x3fb8aa3b, v29
	v_mul_f32_e32 v30, 0x3fb8aa3b, v30
	v_mul_f32_e32 v31, 0x3fb8aa3b, v31
	v_mul_f32_e32 v76, 0x3fb8aa3b, v76
	v_exp_f32_e32 v29, v29
	v_exp_f32_e32 v30, v30
	v_exp_f32_e32 v31, v31
	v_exp_f32_e32 v76, v76
	v_mul_f32_e32 v77, v244, v20
	v_mul_f32_e32 v176, v245, v21
	v_mul_f32_e32 v177, v246, v22
	v_mul_f32_e32 v198, v247, v23
	v_mul_f32_e32 v77, v77, v29
	v_mul_f32_e32 v176, v176, v30
	v_mul_f32_e32 v177, v177, v31
	v_mul_f32_e32 v198, v198, v76
	v_cmp_gt_i32_e32 vcc, s29, v172
	s_nop 1
	v_cndmask_b32_e32 v77, 0, v77, vcc
	v_cmp_gt_i32_e32 vcc, s29, v173
	s_nop 1
	v_cndmask_b32_e32 v176, 0, v176, vcc
	v_cmp_gt_i32_e32 vcc, s29, v174
	s_nop 1
	v_cndmask_b32_e32 v177, 0, v177, vcc
	v_cmp_gt_i32_e32 vcc, s29, v175
	s_nop 1
	v_cndmask_b32_e32 v198, 0, v198, vcc
	ds_write_b32 v171, v77 offset:192
	ds_write_b32 v171, v176 offset:464
	ds_write_b32 v171, v177 offset:736
	ds_write_b32 v171, v198 offset:1008

.Lp3_w1:
	v_add_u32_e32 v157, 0xffffbc00, v157
	v_lshrrev_b32_e32 v156, 2, v154
	v_lshlrev_b32_e32 v156, 4, v156
	v_and_b32_e32 v171, 3, v154
	v_lshl_add_u32 v156, v171, 1, v156
	v_lshl_add_u32 v171, v155, 9, v156
	s_lshl_b32 s0, s64, 13
	s_add_u32 s0, s92, s0
	s_addc_u32 s1, s93, 0
	s_add_u32 s0, s0, 0x1bc00000
	s_addc_u32 s1, s1, 0
	s_lshl_b32 s29, s28, 11
	s_add_u32 s0, s0, s29
	s_addc_u32 s1, s1, 0
	ds_read_b128 v[4:7], v157 offset:0
	ds_read_b128 v[8:11], v157 offset:64
	ds_read_b128 v[12:15], v157 offset:128
	ds_read_b128 v[16:19], v157 offset:192
	ds_read_b128 v[24:27], v169 offset:256
	ds_read_b32 v146, v170 offset:0
	ds_read_b32 v147, v170 offset:64
	ds_read_b32 v148, v170 offset:128
	ds_read_b32 v149, v170 offset:192
	ds_read_b128 v[32:35], v167 offset:0
	ds_read_b128 v[36:39], v167 offset:64
	ds_read_b128 v[40:43], v167 offset:128
	ds_read_b128 v[44:47], v167 offset:192
	s_cmp_lt_u32 s28, 1
	s_cbranch_scc1 .Lp3_w1_a
	ds_read_b128 v[48:51], v167 offset:4352
	ds_read_b128 v[52:55], v167 offset:4416
	ds_read_b128 v[56:59], v167 offset:4480
	ds_read_b128 v[60:63], v167 offset:4544
.Lp3_w1_a:
	s_waitcnt lgkmcnt(0)
	v_mfma_f32_16x16x32_bf16 v[64:67], v[4:7], v[32:35], 0
	v_mfma_f32_16x16x32_bf16 v[64:67], v[8:11], v[36:39], v[64:67]
	v_mfma_f32_16x16x32_bf16 v[64:67], v[12:15], v[40:43], v[64:67]
	v_mfma_f32_16x16x32_bf16 v[64:67], v[16:19], v[44:47], v[64:67]
	s_cmp_lt_u32 s28, 1
	s_cbranch_scc1 .Lp3_w1_b
	v_mfma_f32_16x16x32_bf16 v[68:71], v[4:7], v[48:51], 0
	v_mfma_f32_16x16x32_bf16 v[68:71], v[8:11], v[52:55], v[68:71]
	v_mfma_f32_16x16x32_bf16 v[68:71], v[12:15], v[56:59], v[68:71]
	v_mfma_f32_16x16x32_bf16 v[68:71], v[16:19], v[60:63], v[68:71]
	s_branch .Lp3_w1_c
.Lp3_w1_b:
	v_mov_b32_e32 v68, 0
	v_mov_b32_e32 v69, 0
	v_mov_b32_e32 v70, 0
	v_mov_b32_e32 v71, 0

.Lp3_w1_d:
	s_nop 7
	s_sub_i32 s29, s28, 0
	s_lshl_b32 s29, s29, 4
	s_add_i32 s29, s29, 1
	v_sub_f32_e32 v29, v24, v146
	v_sub_f32_e32 v30, v25, v146
	v_sub_f32_e32 v31, v26, v146
	v_sub_f32_e32 v76, v27, v146
	v_min_f32_e32 v29, 0, v29
	v_min_f32_e32 v30, 0, v30
	v_min_f32_e32 v31, 0, v31
	v_min_f32_e32 v76, 0, v76
	v_mul_f32_e32 v29, 0x3fb8aa3b, v29
	v_mul_f32_e32 v30, 0x3fb8aa3b, v30
	v_mul_f32_e32 v31, 0x3fb8aa3b, v31
	v_mul_f32_e32 v76, 0x3fb8aa3b, v76
	v_exp_f32_e32 v29, v29
	v_exp_f32_e32 v30, v30
	v_exp_f32_e32 v31, v31
	v_exp_f32_e32 v76, v76
	v_mul_f32_e32 v77, v64, v29
	v_mul_f32_e32 v176, v65, v30
	v_mul_f32_e32 v177, v66, v31
	v_mul_f32_e32 v198, v67, v76
	v_cmp_gt_i32_e32 vcc, s29, v172
	s_nop 1
	v_cndmask_b32_e32 v77, 0, v77, vcc
	v_cmp_gt_i32_e32 vcc, s29, v173
	s_nop 1
	v_cndmask_b32_e32 v176, 0, v176, vcc
	v_cmp_gt_i32_e32 vcc, s29, v174
	s_nop 1
	v_cndmask_b32_e32 v177, 0, v177, vcc
	v_cmp_gt_i32_e32 vcc, s29, v175
	s_nop 1
	v_cndmask_b32_e32 v198, 0, v198, vcc
	v_cvt_pk_bf16_f32 v77, v77, v77
	v_cvt_pk_bf16_f32 v176, v176, v176
	v_cvt_pk_bf16_f32 v177, v177, v177
	v_cvt_pk_bf16_f32 v198, v198, v198
	global_store_short v171, v77, s[0:1] offset:0
	global_store_short v171, v176, s[0:1] offset:128
	global_store_short v171, v177, s[0:1] offset:256
	global_store_short v171, v198, s[0:1] offset:384
	s_sub_i32 s29, s28, 1
	s_lshl_b32 s29, s29, 4
	s_add_i32 s29, s29, 1
	v_sub_f32_e32 v29, v24, v147
	v_sub_f32_e32 v30, v25, v147
	v_sub_f32_e32 v31, v26, v147
	v_sub_f32_e32 v76, v27, v147
	v_min_f32_e32 v29, 0, v29
	v_min_f32_e32 v30, 0, v30
	v_min_f32_e32 v31, 0, v31
	v_min_f32_e32 v76, 0, v76
	v_mul_f32_e32 v29, 0x3fb8aa3b, v29
	v_mul_f32_e32 v30, 0x3fb8aa3b, v30
	v_mul_f32_e32 v31, 0x3fb8aa3b, v31
	v_mul_f32_e32 v76, 0x3fb8aa3b, v76
	v_exp_f32_e32 v29, v29
	v_exp_f32_e32 v30, v30
	v_exp_f32_e32 v31, v31
	v_exp_f32_e32 v76, v76
	v_mul_f32_e32 v77, v68, v29
	v_mul_f32_e32 v176, v69, v30
	v_mul_f32_e32 v177, v70, v31
	v_mul_f32_e32 v198, v71, v76
	v_cmp_gt_i32_e32 vcc, s29, v172
	s_nop 1
	v_cndmask_b32_e32 v77, 0, v77, vcc
	v_cmp_gt_i32_e32 vcc, s29, v173
	s_nop 1
	v_cndmask_b32_e32 v176, 0, v176, vcc
	v_cmp_gt_i32_e32 vcc, s29, v174
	s_nop 1
	v_cndmask_b32_e32 v177, 0, v177, vcc
	v_cmp_gt_i32_e32 vcc, s29, v175
	s_nop 1
	v_cndmask_b32_e32 v198, 0, v198, vcc
	v_cvt_pk_bf16_f32 v77, v77, v77
	v_cvt_pk_bf16_f32 v176, v176, v176
	v_cvt_pk_bf16_f32 v177, v177, v177
	v_cvt_pk_bf16_f32 v198, v198, v198
	global_store_short v171, v77, s[0:1] offset:8
	global_store_short v171, v176, s[0:1] offset:136
	global_store_short v171, v177, s[0:1] offset:264
	global_store_short v171, v198, s[0:1] offset:392
	s_waitcnt lgkmcnt(0)
	s_cmp_lt_u32 s28, 2
	s_cbranch_scc1 .Lp3_w1_z2
	v_mfma_f32_16x16x32_bf16 v[72:75], v[4:7], v[32:35], 0
	v_mfma_f32_16x16x32_bf16 v[72:75], v[8:11], v[36:39], v[72:75]
	v_mfma_f32_16x16x32_bf16 v[72:75], v[12:15], v[40:43], v[72:75]
	v_mfma_f32_16x16x32_bf16 v[72:75], v[16:19], v[44:47], v[72:75]
	s_cmp_lt_u32 s28, 3
	s_cbranch_scc1 .Lp3_w1_z3
	v_mfma_f32_16x16x32_bf16 v[20:23], v[4:7], v[48:51], 0
	v_mfma_f32_16x16x32_bf16 v[20:23], v[8:11], v[52:55], v[20:23]
	v_mfma_f32_16x16x32_bf16 v[20:23], v[12:15], v[56:59], v[20:23]
	v_mfma_f32_16x16x32_bf16 v[20:23], v[16:19], v[60:63], v[20:23]
	s_branch .Lp3_w1_e
.Lp3_w1_z2:
	v_mov_b32_e32 v72, 0
	v_mov_b32_e32 v73, 0
	v_mov_b32_e32 v74, 0
	v_mov_b32_e32 v75, 0
.Lp3_w1_z3:
	v_mov_b32_e32 v20, 0
	v_mov_b32_e32 v21, 0
	v_mov_b32_e32 v22, 0
	v_mov_b32_e32 v23, 0
.Lp3_w1_e:
	s_nop 7
	s_sub_i32 s29, s28, 2
	s_lshl_b32 s29, s29, 4
	s_add_i32 s29, s29, 1
	v_sub_f32_e32 v29, v24, v148
	v_sub_f32_e32 v30, v25, v148
	v_sub_f32_e32 v31, v26, v148
	v_sub_f32_e32 v76, v27, v148
	v_min_f32_e32 v29, 0, v29
	v_min_f32_e32 v30, 0, v30
	v_min_f32_e32 v31, 0, v31
	v_min_f32_e32 v76, 0, v76
	v_mul_f32_e32 v29, 0x3fb8aa3b, v29
	v_mul_f32_e32 v30, 0x3fb8aa3b, v30
	v_mul_f32_e32 v31, 0x3fb8aa3b, v31
	v_mul_f32_e32 v76, 0x3fb8aa3b, v76
	v_exp_f32_e32 v29, v29
	v_exp_f32_e32 v30, v30
	v_exp_f32_e32 v31, v31
	v_exp_f32_e32 v76, v76
	v_mul_f32_e32 v77, v72, v29
	v_mul_f32_e32 v176, v73, v30
	v_mul_f32_e32 v177, v74, v31
	v_mul_f32_e32 v198, v75, v76
	v_cmp_gt_i32_e32 vcc, s29, v172
	s_nop 1
	v_cndmask_b32_e32 v77, 0, v77, vcc
	v_cmp_gt_i32_e32 vcc, s29, v173
	s_nop 1
	v_cndmask_b32_e32 v176, 0, v176, vcc
	v_cmp_gt_i32_e32 vcc, s29, v174
	s_nop 1
	v_cndmask_b32_e32 v177, 0, v177, vcc
	v_cmp_gt_i32_e32 vcc, s29, v175
	s_nop 1
	v_cndmask_b32_e32 v198, 0, v198, vcc
	v_cvt_pk_bf16_f32 v77, v77, v77
	v_cvt_pk_bf16_f32 v176, v176, v176
	v_cvt_pk_bf16_f32 v177, v177, v177
	v_cvt_pk_bf16_f32 v198, v198, v198
	global_store_short v171, v77, s[0:1] offset:64
	global_store_short v171, v176, s[0:1] offset:192
	global_store_short v171, v177, s[0:1] offset:320
	global_store_short v171, v198, s[0:1] offset:448
	s_sub_i32 s29, s28, 3
	s_lshl_b32 s29, s29, 4
	s_add_i32 s29, s29, 1
	v_sub_f32_e32 v29, v24, v149
	v_sub_f32_e32 v30, v25, v149
	v_sub_f32_e32 v31, v26, v149
	v_sub_f32_e32 v76, v27, v149
	v_min_f32_e32 v29, 0, v29
	v_min_f32_e32 v30, 0, v30
	v_min_f32_e32 v31, 0, v31
	v_min_f32_e32 v76, 0, v76
	v_mul_f32_e32 v29, 0x3fb8aa3b, v29
	v_mul_f32_e32 v30, 0x3fb8aa3b, v30
	v_mul_f32_e32 v31, 0x3fb8aa3b, v31
	v_mul_f32_e32 v76, 0x3fb8aa3b, v76
	v_exp_f32_e32 v29, v29
	v_exp_f32_e32 v30, v30
	v_exp_f32_e32 v31, v31
	v_exp_f32_e32 v76, v76
	v_mul_f32_e32 v77, v20, v29
	v_mul_f32_e32 v176, v21, v30
	v_mul_f32_e32 v177, v22, v31
	v_mul_f32_e32 v198, v23, v76
	v_cmp_gt_i32_e32 vcc, s29, v172
	s_nop 1
	v_cndmask_b32_e32 v77, 0, v77, vcc
	v_cmp_gt_i32_e32 vcc, s29, v173
	s_nop 1
	v_cndmask_b32_e32 v176, 0, v176, vcc
	v_cmp_gt_i32_e32 vcc, s29, v174
	s_nop 1
	v_cndmask_b32_e32 v177, 0, v177, vcc
	v_cmp_gt_i32_e32 vcc, s29, v175
	s_nop 1
	v_cndmask_b32_e32 v198, 0, v198, vcc
	v_cvt_pk_bf16_f32 v77, v77, v77
	v_cvt_pk_bf16_f32 v176, v176, v176
	v_cvt_pk_bf16_f32 v177, v177, v177
	v_cvt_pk_bf16_f32 v198, v198, v198
	global_store_short v171, v77, s[0:1] offset:72
	global_store_short v171, v176, s[0:1] offset:200
	global_store_short v171, v177, s[0:1] offset:328
	global_store_short v171, v198, s[0:1] offset:456
.Lp3_w1_done:
.Lp3_end:
.LBB0_335:
	s_waitcnt lgkmcnt(0)
	s_barrier
	s_lshl_b64 s[0:1], s[64:65], 14
	s_mov_b64 s[28:29], -1
	s_and_b64 vcc, exec, s[40:41]
	s_cbranch_vccz .LBB0_339
	v_lshlrev_b32_e32 v5, 2, v182
	v_add_u32_e32 v4, 0x215fc, v234
	v_add3_u32 v8, v234, v197, v5
	v_lshl_add_u32 v10, v196, 2, v239
	ds_read_b32 v4, v4
	ds_read2_b32 v[6:7], v10 offset0:64 offset1:65
	ds_read2st64_b32 v[8:9], v8 offset0:132 offset1:165
	v_lshl_add_u32 v18, v215, 2, v239
	ds_read2_b32 v[10:11], v10 offset0:80 offset1:81
	ds_read2_b32 v[12:13], v18 offset0:64 offset1:65
	v_add3_u32 v14, v234, v252, v5
	ds_read2st64_b32 v[14:15], v14 offset0:132 offset1:165
	s_waitcnt lgkmcnt(0)
	v_mov_b32_e32 v16, v8
	v_sub_f32_e32 v10, v4, v10
	v_sub_f32_e32 v8, v4, v11
	v_mul_f32_e32 v10, 0x3fb8aa3b, v10
	v_mul_f32_e32 v8, 0x3fb8aa3b, v8
	v_exp_f32_e32 v10, v10
	v_exp_f32_e32 v11, v8
	v_sub_f32_e32 v6, v4, v6
	v_sub_f32_e32 v7, v4, v7
	v_mul_f32_e32 v6, 0x3fb8aa3b, v6
	v_mul_f32_e32 v7, 0x3fb8aa3b, v7
	v_mov_b32_e32 v17, v14
	v_mov_b32_e32 v14, v9
	v_exp_f32_e32 v6, v6
	v_exp_f32_e32 v7, v7
	v_pk_mul_f32 v[8:9], v[14:15], v[10:11]
	v_add3_u32 v14, v234, v200, v5
	ds_read2_b32 v[10:11], v18 offset0:80 offset1:81
	ds_read2st64_b32 v[14:15], v14 offset0:132 offset1:165
	v_pk_mul_f32 v[6:7], v[16:17], v[6:7]
	v_add3_u32 v16, v234, v201, v5
	ds_read2st64_b32 v[16:17], v16 offset0:132 offset1:165
	s_waitcnt lgkmcnt(0)
	v_sub_f32_e32 v10, v4, v10
	v_sub_f32_e32 v11, v4, v11
	v_sub_f32_e32 v12, v4, v12
	v_mul_f32_e32 v10, 0x3fb8aa3b, v10
	v_sub_f32_e32 v13, v4, v13
	v_mul_f32_e32 v11, 0x3fb8aa3b, v11
	v_mul_f32_e32 v12, 0x3fb8aa3b, v12
	v_exp_f32_e32 v10, v10
	v_mul_f32_e32 v13, 0x3fb8aa3b, v13
	v_exp_f32_e32 v11, v11
	v_exp_f32_e32 v12, v12
	v_exp_f32_e32 v13, v13
	v_mov_b32_e32 v19, v16
	v_mov_b32_e32 v16, v15
	v_lshl_add_u64 v[2:3], v[82:83], 0, s[0:1]
	v_mov_b32_e32 v18, v14
	v_pk_mul_f32 v[10:11], v[16:17], v[10:11]
	v_pk_mul_f32 v[12:13], v[18:19], v[12:13]
	v_cvt_pk_bf16_f32 v8, v8, v9
	v_cvt_pk_bf16_f32 v9, v10, v11
	v_lshl_add_u64 v[10:11], v[130:131], 1, v[2:3]
	v_cvt_pk_bf16_f32 v6, v6, v7
	v_cvt_pk_bf16_f32 v7, v12, v13
	v_lshl_add_u64 v[10:11], v[10:11], 0, v[0:1]
	flat_store_dwordx4 v[10:11], v[6:9]
	v_lshl_add_u32 v10, v202, 2, v239
	v_lshl_add_u32 v14, v205, 2, v239
	v_add3_u32 v6, v234, v203, v5
	ds_read2st64_b32 v[6:7], v6 offset0:132 offset1:165
	ds_read2_b32 v[8:9], v10 offset0:64 offset1:65
	ds_read2_b32 v[10:11], v10 offset0:80 offset1:81
	ds_read2_b32 v[12:13], v14 offset0:64 offset1:65
	ds_read2_b32 v[14:15], v14 offset0:80 offset1:81
	v_add3_u32 v16, v234, v204, v5
	ds_read2st64_b32 v[16:17], v16 offset0:132 offset1:165
	s_waitcnt lgkmcnt(0)
	v_mov_b32_e32 v18, v6
	v_sub_f32_e32 v6, v4, v11
	v_sub_f32_e32 v10, v4, v10
	v_mul_f32_e32 v6, 0x3fb8aa3b, v6
	v_sub_f32_e32 v8, v4, v8
	v_mul_f32_e32 v10, 0x3fb8aa3b, v10
	v_sub_f32_e32 v9, v4, v9
	v_exp_f32_e32 v11, v6
	v_add3_u32 v6, v234, v206, v5
	v_mul_f32_e32 v8, 0x3fb8aa3b, v8
	v_exp_f32_e32 v10, v10
	v_mul_f32_e32 v9, 0x3fb8aa3b, v9
	v_mov_b32_e32 v19, v16
	v_mov_b32_e32 v16, v7
	ds_read2st64_b32 v[6:7], v6 offset0:132 offset1:165
	v_exp_f32_e32 v8, v8
	v_exp_f32_e32 v9, v9
	v_pk_mul_f32 v[10:11], v[16:17], v[10:11]
	v_add3_u32 v16, v234, v207, v5
	v_sub_f32_e32 v12, v4, v12
	v_pk_mul_f32 v[8:9], v[18:19], v[8:9]
	v_sub_f32_e32 v14, v4, v14
	ds_read2st64_b32 v[16:17], v16 offset0:132 offset1:165
	v_sub_f32_e32 v13, v4, v13
	s_waitcnt lgkmcnt(0)
	v_mov_b32_e32 v18, v6
	v_sub_f32_e32 v6, v4, v15
	v_mul_f32_e32 v12, 0x3fb8aa3b, v12
	v_mul_f32_e32 v14, 0x3fb8aa3b, v14
	v_mul_f32_e32 v13, 0x3fb8aa3b, v13
	v_mul_f32_e32 v6, 0x3fb8aa3b, v6
	v_exp_f32_e32 v12, v12
	v_exp_f32_e32 v14, v14
	v_exp_f32_e32 v13, v13
	v_exp_f32_e32 v15, v6
	v_mov_b32_e32 v19, v16
	v_mov_b32_e32 v16, v7
	v_pk_mul_f32 v[12:13], v[18:19], v[12:13]
	v_pk_mul_f32 v[14:15], v[16:17], v[14:15]
	v_cvt_pk_bf16_f32 v6, v8, v9
	v_cvt_pk_bf16_f32 v8, v10, v11
	v_lshl_add_u64 v[10:11], v[132:133], 1, v[2:3]
	v_mov_b32_e32 v167, v1
	v_cvt_pk_bf16_f32 v7, v12, v13
	v_cvt_pk_bf16_f32 v9, v14, v15
	v_lshl_add_u64 v[10:11], v[10:11], 0, v[166:167]
	flat_store_dwordx4 v[10:11], v[6:9]
	v_lshl_add_u32 v10, v208, 2, v239
	v_lshl_add_u32 v14, v211, 2, v239
	v_add3_u32 v6, v234, v209, v5
	ds_read2st64_b32 v[6:7], v6 offset0:132 offset1:165
	ds_read2_b32 v[8:9], v10 offset0:64 offset1:65
	ds_read2_b32 v[10:11], v10 offset0:80 offset1:81
	ds_read2_b32 v[12:13], v14 offset0:64 offset1:65
	ds_read2_b32 v[14:15], v14 offset0:80 offset1:81
	v_add3_u32 v16, v234, v210, v5
	ds_read2st64_b32 v[16:17], v16 offset0:132 offset1:165
	s_waitcnt lgkmcnt(0)
	v_mov_b32_e32 v18, v6
	v_sub_f32_e32 v6, v4, v11
	v_sub_f32_e32 v10, v4, v10
	v_mul_f32_e32 v6, 0x3fb8aa3b, v6
	v_sub_f32_e32 v8, v4, v8
	v_mul_f32_e32 v10, 0x3fb8aa3b, v10
	v_sub_f32_e32 v9, v4, v9
	v_exp_f32_e32 v11, v6
	v_add3_u32 v6, v234, v212, v5
	v_mul_f32_e32 v8, 0x3fb8aa3b, v8
	v_exp_f32_e32 v10, v10
	v_mul_f32_e32 v9, 0x3fb8aa3b, v9
	v_mov_b32_e32 v19, v16
	v_mov_b32_e32 v16, v7
	ds_read2st64_b32 v[6:7], v6 offset0:132 offset1:165
	v_exp_f32_e32 v8, v8
	v_exp_f32_e32 v9, v9
	v_pk_mul_f32 v[10:11], v[16:17], v[10:11]
	v_add3_u32 v16, v234, v213, v5
	v_sub_f32_e32 v12, v4, v12
	v_pk_mul_f32 v[8:9], v[18:19], v[8:9]
	v_sub_f32_e32 v14, v4, v14
	ds_read2st64_b32 v[16:17], v16 offset0:132 offset1:165
	v_sub_f32_e32 v13, v4, v13
	s_waitcnt lgkmcnt(0)
	v_mov_b32_e32 v18, v6
	v_sub_f32_e32 v6, v4, v15
	v_mul_f32_e32 v12, 0x3fb8aa3b, v12
	v_mul_f32_e32 v14, 0x3fb8aa3b, v14
	v_mul_f32_e32 v13, 0x3fb8aa3b, v13
	v_mul_f32_e32 v6, 0x3fb8aa3b, v6
	v_exp_f32_e32 v12, v12
	v_exp_f32_e32 v14, v14
	v_exp_f32_e32 v13, v13
	v_exp_f32_e32 v15, v6
	v_mov_b32_e32 v19, v16
	v_mov_b32_e32 v16, v7
	v_pk_mul_f32 v[12:13], v[18:19], v[12:13]
	v_pk_mul_f32 v[14:15], v[16:17], v[14:15]
	v_cvt_pk_bf16_f32 v6, v8, v9
	v_cvt_pk_bf16_f32 v8, v10, v11
	v_lshl_add_u64 v[10:11], v[134:135], 1, v[2:3]
	v_mov_b32_e32 v169, v1
	v_cvt_pk_bf16_f32 v7, v12, v13
	v_cvt_pk_bf16_f32 v9, v14, v15
	v_lshl_add_u64 v[10:11], v[10:11], 0, v[168:169]
	flat_store_dwordx4 v[10:11], v[6:9]
	v_lshl_add_u32 v10, v221, 2, v239
	v_lshl_add_u32 v14, v224, 2, v239
	v_add3_u32 v6, v234, v222, v5
	ds_read2st64_b32 v[6:7], v6 offset0:132 offset1:165
	ds_read2_b32 v[8:9], v10 offset0:64 offset1:65
	ds_read2_b32 v[10:11], v10 offset0:80 offset1:81
	ds_read2_b32 v[12:13], v14 offset0:64 offset1:65
	ds_read2_b32 v[14:15], v14 offset0:80 offset1:81
	v_add3_u32 v16, v234, v223, v5
	ds_read2st64_b32 v[16:17], v16 offset0:132 offset1:165
	s_waitcnt lgkmcnt(0)
	v_sub_f32_e32 v10, v4, v10
	v_mov_b32_e32 v18, v6
	v_sub_f32_e32 v6, v4, v11
	v_mul_f32_e32 v10, 0x3fb8aa3b, v10
	v_mul_f32_e32 v6, 0x3fb8aa3b, v6
	v_exp_f32_e32 v10, v10
	v_exp_f32_e32 v11, v6
	v_mov_b32_e32 v19, v16
	v_mov_b32_e32 v16, v7
	v_add3_u32 v6, v234, v225, v5
	v_add3_u32 v5, v234, v226, v5
	v_pk_mul_f32 v[10:11], v[16:17], v[10:11]
	ds_read2st64_b32 v[16:17], v5 offset0:132 offset1:165
	v_sub_f32_e32 v5, v4, v13
	v_sub_f32_e32 v8, v4, v8
	v_sub_f32_e32 v9, v4, v9
	v_mul_f32_e32 v5, 0x3fb8aa3b, v5
	v_mul_f32_e32 v8, 0x3fb8aa3b, v8
	v_mul_f32_e32 v9, 0x3fb8aa3b, v9
	ds_read2st64_b32 v[6:7], v6 offset0:132 offset1:165
	v_sub_f32_e32 v12, v4, v12
	v_sub_f32_e32 v14, v4, v14
	v_exp_f32_e32 v13, v5
	v_sub_f32_e32 v5, v4, v15
	v_exp_f32_e32 v8, v8
	v_exp_f32_e32 v9, v9
	v_mul_f32_e32 v12, 0x3fb8aa3b, v12
	v_mul_f32_e32 v14, 0x3fb8aa3b, v14
	v_mul_f32_e32 v5, 0x3fb8aa3b, v5
	v_exp_f32_e32 v12, v12
	v_exp_f32_e32 v14, v14
	v_exp_f32_e32 v15, v5
	v_pk_mul_f32 v[8:9], v[18:19], v[8:9]
	s_waitcnt lgkmcnt(0)
	v_mov_b32_e32 v18, v6
	v_mov_b32_e32 v19, v16
	v_mov_b32_e32 v16, v7
	v_pk_mul_f32 v[12:13], v[18:19], v[12:13]
	v_pk_mul_f32 v[14:15], v[16:17], v[14:15]
	v_lshl_add_u64 v[2:3], v[136:137], 1, v[2:3]
	v_cvt_pk_bf16_f32 v6, v8, v9
	v_cvt_pk_bf16_f32 v7, v12, v13
	v_cvt_pk_bf16_f32 v8, v10, v11
	v_cvt_pk_bf16_f32 v9, v14, v15
	v_lshl_add_u64 v[2:3], v[2:3], 0, v[166:167]
	flat_store_dwordx4 v[2:3], v[6:9]
	s_and_saveexec_b64 s[28:29], s[24:25]
	s_cbranch_execz .LBB0_338
	v_mul_f32_e32 v2, 0x3fb8aa3b, v4
	v_rndne_f32_e32 v3, v2
	v_sub_f32_e32 v5, v2, v3
	v_fma_f32 v2, v4, s21, -v2
	v_fmac_f32_e32 v2, 0x32a5705f, v4
	v_add_f32_e32 v2, v5, v2
	v_cvt_i32_f32_e32 v3, v3
	v_exp_f32_e32 v2, v2
	v_cmp_ngt_f32_e32 vcc, s22, v4
	s_mov_b32 s12, 0x42b17218
	s_lshl_b64 s[30:31], s[64:65], 2
	v_ldexp_f32 v2, v2, v3
	v_cndmask_b32_e32 v2, 0, v2, vcc
	v_cmp_nlt_f32_e32 vcc, s12, v4
	v_readlane_b32 s12, v254, 58
	s_add_u32 s30, s12, s30
	v_readlane_b32 s12, v254, 59
	s_addc_u32 s31, s12, s31
	v_cndmask_b32_e32 v4, v219, v2, vcc
	v_mov_b64_e32 v[2:3], s[30:31]
	flat_store_dword v[2:3], v4
